# attention: LDS-DMA addresses as SGPR base + 32-bit lane offset (no v_lshl_add_u64), single-copy cross-half row max, permlane wait states re-derived
# speedup vs baseline: 1.0055x; 1.0055x over previous
.LBB0_999:
	v_mfma_f32_32x32x16_bf16 v[4:19], v[80:83], v[180:183], v[4:19]
	global_load_lds_dwordx4 v190, s[48:49]
	s_cselect_b32 s49, s49, s51
	s_cselect_b32 s48, s48, s50
	s_cselect_b32 s43, s38, s40
	s_add_i32 m0, s21, s43
	s_add_i32 s43, s23, s40
	global_load_lds_dwordx4 v192, s[48:49]
	s_add_i32 m0, s43, 0xd000
	s_mov_b32 s43, s39
	global_load_lds_dwordx4 v194, s[50:51]
	s_mov_b32 s39, s44
	s_mov_b32 s44, s15
	s_mov_b32 s45, s14
	v_max3_f32 v2, v52, v36, v53
	s_nop 0
	v_max3_f32 v2, v2, v37, v54
	v_mfma_f32_32x32x16_bf16 v[20:35], v[80:83], v[164:167], v[20:35]
	s_nop 0
	v_max3_f32 v2, v2, v38, v55
	s_nop 0
	v_max3_f32 v2, v2, v39, v56
	v_max3_f32 v68, v60, v44, v61
	v_max3_f32 v2, v2, v40, v57
	v_mfma_f32_32x32x16_bf16 v[4:19], v[76:79], v[176:179], v[4:19]
	s_nop 0
	v_max3_f32 v68, v68, v45, v62
	v_max3_f32 v2, v2, v41, v58
	s_nop 0
	v_max3_f32 v68, v68, v46, v63
	v_max3_f32 v68, v68, v47, v64
	v_mfma_f32_32x32x16_bf16 v[20:35], v[76:79], v[156:159], v[20:35]
	v_max3_f32 v2, v2, v42, v59
	v_max3_f32 v68, v68, v48, v65
	s_nop 0
	v_max3_f32 v68, v68, v49, v66
	v_max3_f32 v68, v68, v50, v67
	s_nop 0
	v_mfma_f32_32x32x16_bf16 v[20:35], v[72:75], v[152:155], v[20:35]
	v_max3_f32 v2, v2, v43, v68
	s_nop 0
	v_max3_f32 v2, v2, v51, v2
	s_nop 0
	v_mov_b32_e32 v69, v2
	v_mfma_f32_32x32x16_bf16 v[4:19], v[72:75], v[148:151], v[4:19]
	s_nop 1
	v_permlane32_swap_b32_e32 v2, v69
	v_max3_f32 v2, v2, v69, v2
	s_nop 0
	v_cmp_lt_f32_e32 vcc, s56, v2
	s_cbranch_vccz .LBB0_1003
	v_add_f32_e32 v180, v210, v2
	v_cvt_pk_bf16_f32 v180, v180, v180
	v_lshlrev_b32_e32 v180, 16, v180
	v_cndmask_b32_e32 v180, v210, v180, vcc
	v_sub_f32_e32 v2, v210, v180
	v_sub_f32_e32 v84, v180, v210
	v_xor_b32_e32 v250, 0x80000000, v180
	v_min_f32_e32 v2, 0, v2
	v_lshrrev_b32_e32 v250, 16, v250
	v_exp_f32_e32 v2, v2
	v_cndmask_b32_e64 v250, 0, v250, s[2:3]
	s_and_saveexec_b64 s[14:15], s[2:3]
	ds_write_b32 v202, v2
	s_or_b64 exec, exec, s[14:15]
	ds_read_b32 v68, v1
	ds_read_b32 v69, v1 offset:4
	ds_read_b32 v70, v1 offset:8
	ds_read_b32 v71, v1 offset:12
	ds_read_b32 v72, v1 offset:32
	ds_read_b32 v73, v1 offset:36
	ds_read_b32 v74, v1 offset:40
	ds_read_b32 v75, v1 offset:44
	ds_read_b32 v76, v1 offset:64
	ds_read_b32 v77, v1 offset:68
	ds_read_b32 v78, v1 offset:72
	ds_read_b32 v79, v1 offset:76
	ds_read_b32 v80, v1 offset:96
	ds_read_b32 v81, v1 offset:100
	ds_read_b32 v82, v1 offset:104
	ds_read_b32 v83, v1 offset:108
	v_mul_f32_e32 v209, v209, v2
	s_waitcnt lgkmcnt(0)
	v_pk_mul_f32 v[20:21], v[20:21], v[68:69]
	v_pk_mul_f32 v[22:23], v[22:23], v[70:71]
	v_pk_mul_f32 v[24:25], v[24:25], v[72:73]
	v_pk_mul_f32 v[26:27], v[26:27], v[74:75]
	v_pk_mul_f32 v[28:29], v[28:29], v[76:77]
	v_pk_mul_f32 v[30:31], v[30:31], v[78:79]
	v_pk_mul_f32 v[32:33], v[32:33], v[80:81]
	v_pk_mul_f32 v[34:35], v[34:35], v[82:83]
	v_pk_mul_f32 v[4:5], v[4:5], v[68:69]
	v_pk_mul_f32 v[6:7], v[6:7], v[70:71]
	v_pk_mul_f32 v[8:9], v[8:9], v[72:73]
	v_pk_mul_f32 v[10:11], v[10:11], v[74:75]
	v_pk_mul_f32 v[12:13], v[12:13], v[76:77]
	v_pk_mul_f32 v[14:15], v[14:15], v[78:79]
	v_pk_mul_f32 v[16:17], v[16:17], v[80:81]
	v_pk_mul_f32 v[18:19], v[18:19], v[82:83]
	v_sub_f32_e32 v36, v36, v84
	v_sub_f32_e32 v37, v37, v84
	v_sub_f32_e32 v38, v38, v84
	v_sub_f32_e32 v39, v39, v84
	v_sub_f32_e32 v40, v40, v84
	v_sub_f32_e32 v41, v41, v84
	v_sub_f32_e32 v42, v42, v84
	v_sub_f32_e32 v43, v43, v84
	v_sub_f32_e32 v44, v44, v84
	v_sub_f32_e32 v45, v45, v84
	v_sub_f32_e32 v46, v46, v84
	v_sub_f32_e32 v47, v47, v84
	v_sub_f32_e32 v48, v48, v84
	v_sub_f32_e32 v49, v49, v84
	v_sub_f32_e32 v50, v50, v84
	v_sub_f32_e32 v51, v51, v84
	v_sub_f32_e32 v52, v52, v84
	v_sub_f32_e32 v53, v53, v84
	v_sub_f32_e32 v54, v54, v84
	v_sub_f32_e32 v55, v55, v84
	v_sub_f32_e32 v56, v56, v84
	v_sub_f32_e32 v57, v57, v84
	v_sub_f32_e32 v58, v58, v84
	v_sub_f32_e32 v59, v59, v84
	v_sub_f32_e32 v60, v60, v84
	v_sub_f32_e32 v61, v61, v84
	v_sub_f32_e32 v62, v62, v84
	v_sub_f32_e32 v63, v63, v84
	v_sub_f32_e32 v64, v64, v84
	v_sub_f32_e32 v65, v65, v84
	v_sub_f32_e32 v66, v66, v84
	v_sub_f32_e32 v67, v67, v84
	s_mov_b32 s56, 0x41000000
	s_branch .LBB0_1004

.LBB0_1004:
	v_mfma_f32_32x32x16_bf16 v[68:83], v[246:249], v[250:253], 0
	v_mfma_f32_32x32x16_bf16 v[68:83], v[136:139], v[100:103], v[68:83]
	v_add_u32_e32 v2, s45, v189
	ds_read_b128 v[184:187], v2 offset:96
	ds_read_b128 v[210:213], v2 offset:128
	ds_read_b128 v[214:217], v2 offset:6752
	ds_read_b128 v[218:221], v2 offset:160
	ds_read_b128 v[222:225], v2 offset:6784
	ds_read_b128 v[226:229], v2 offset:6816
	v_add_u32_e32 v2, s39, v200
	ds_read_b128 v[176:179], v2 offset:53248
	ds_read_b128 v[164:167], v2 offset:53280
	ds_read_b128 v[230:233], v2 offset:57856
	ds_read_b128 v[238:241], v2 offset:57888
	ds_read_b128 v[160:163], v2 offset:53312
	ds_read_b128 v[156:159], v2 offset:53344
	ds_read_b128 v[242:245], v2 offset:57920
	ds_read_b128 v[152:155], v2 offset:57952
	v_mfma_f32_32x32x16_bf16 v[84:99], v[246:249], v[250:253], 0
	v_mfma_f32_32x32x16_bf16 v[84:99], v[132:135], v[100:103], v[84:99]
	v_exp_f32_e32 v52, v52
	v_exp_f32_e32 v183, v36
	v_exp_f32_e32 v132, v53
	v_exp_f32_e32 v53, v54
	v_mfma_f32_32x32x16_bf16 v[68:83], v[144:147], v[104:107], v[68:83]
	v_exp_f32_e32 v54, v38
	v_exp_f32_e32 v36, v55
	v_exp_f32_e32 v55, v56
	v_exp_f32_e32 v56, v40
	v_mfma_f32_32x32x16_bf16 v[84:99], v[128:131], v[104:107], v[84:99]
	v_exp_f32_e32 v40, v39
	v_exp_f32_e32 v38, v57
	v_exp_f32_e32 v57, v58
	v_exp_f32_e32 v58, v41
	v_mfma_f32_32x32x16_bf16 v[68:83], v[140:143], v[108:111], v[68:83]
	v_add_u32_e32 v181, s44, v189
	ds_read_b128 v[144:147], v181
	ds_read_b128 v[172:175], v181 offset:32
	ds_read_b128 v[136:139], v181 offset:6656
	ds_read_b128 v[168:171], v181 offset:64
	ds_read_b128 v[148:151], v181 offset:6688
	ds_read_b128 v[140:143], v181 offset:6720
	v_exp_f32_e32 v2, v37
	v_mfma_f32_32x32x16_bf16 v[84:99], v[124:127], v[108:111], v[84:99]
	v_exp_f32_e32 v124, v59
	v_exp_f32_e32 v41, v60
	v_add_f32_e32 v133, v52, v183
	v_add_f32_e32 v37, v53, v54
	s_waitcnt lgkmcnt(14)
	v_mfma_f32_32x32x16_bf16 v[68:83], v[214:217], v[112:115], v[68:83]
	v_exp_f32_e32 v214, v42
	v_exp_f32_e32 v59, v44
	v_exp_f32_e32 v60, v43
	v_exp_f32_e32 v126, v61
	v_mfma_f32_32x32x16_bf16 v[84:99], v[184:187], v[112:115], v[84:99]
	v_exp_f32_e32 v61, v62
	v_exp_f32_e32 v62, v45
	v_exp_f32_e32 v128, v63
	v_exp_f32_e32 v63, v64
	v_mfma_f32_32x32x16_bf16 v[68:83], v[222:225], v[116:119], v[68:83]
	v_exp_f32_e32 v216, v48
	v_exp_f32_e32 v64, v47
	v_exp_f32_e32 v130, v65
	v_mfma_f32_32x32x16_bf16 v[84:99], v[210:213], v[116:119], v[84:99]
	v_exp_f32_e32 v65, v66
	v_exp_f32_e32 v215, v46
	v_exp_f32_e32 v185, v50
	v_mfma_f32_32x32x16_bf16 v[68:83], v[226:229], v[120:123], v[68:83]
	v_exp_f32_e32 v66, v49
	v_exp_f32_e32 v134, v67
	v_add_f32_e32 v39, v55, v56
	v_add_f32_e32 v125, v57, v214
	v_mfma_f32_32x32x16_bf16 v[84:99], v[218:221], v[120:123], v[84:99]
	v_add_f32_e32 v127, v41, v59
	v_add_f32_e32 v129, v61, v215
	v_add_f32_e32 v131, v63, v216
	v_add_f32_e32 v135, v65, v185
	v_exp_f32_e32 v184, v51
	v_cvt_pk_bf16_f32 v42, v52, v132
	v_cvt_pk_bf16_f32 v43, v53, v36
	v_cvt_pk_bf16_f32 v44, v55, v38
	v_cvt_pk_bf16_f32 v45, v57, v124
	v_cvt_pk_bf16_f32 v46, v41, v126
	v_cvt_pk_bf16_f32 v47, v61, v128
	s_waitcnt lgkmcnt(11)
	v_mfma_f32_32x32x16_bf16 v[4:19], v[42:45], v[230:233], v[4:19]
	v_cvt_pk_bf16_f32 v48, v63, v130
	v_cvt_pk_bf16_f32 v49, v65, v134
	v_cvt_pk_bf16_f32 v50, v183, v2
	v_cvt_pk_bf16_f32 v51, v54, v40
	v_cvt_pk_bf16_f32 v52, v56, v58
	v_cvt_pk_bf16_f32 v53, v214, v60
	v_mfma_f32_32x32x16_bf16 v[20:35], v[42:45], v[176:179], v[20:35]
	v_cvt_pk_bf16_f32 v54, v59, v62
	v_cvt_pk_bf16_f32 v55, v215, v64
	v_cvt_pk_bf16_f32 v56, v216, v66
	v_cvt_pk_bf16_f32 v57, v185, v184
	s_add_i32 s14, s46, 5
	s_min_u32 s14, s14, s37
	s_add_i32 s15, s46, 3
	s_min_u32 s46, s15, s37
	s_mulk_i32 s14, 0x3000
	s_add_u32 s14, s10, s14
	s_addc_u32 s15, s11, 0
	s_lshl_b32 s46, s46, 13
	s_add_u32 s46, s12, s46
	s_addc_u32 s47, s13, 0
	s_add_i32 m0, s22, s45
	s_and_b64 s[48:49], s[4:5], exec
	s_waitcnt vmcnt(3) lgkmcnt(0)
	s_barrier
	v_mfma_f32_32x32x16_bf16 v[4:19], v[46:49], v[238:241], v[4:19]
	global_load_lds_dwordx4 v190, s[14:15]
	s_cselect_b32 s15, s15, s47
	s_cselect_b32 s14, s14, s46
	s_cselect_b32 s98, s45, s39
	s_add_i32 m0, s21, s98
	s_add_i32 s98, s23, s39
	global_load_lds_dwordx4 v192, s[14:15]
	s_add_i32 m0, s98, 0xd000
	s_nop 0
	global_load_lds_dwordx4 v194, s[46:47]
	v_max3_f32 v41, v84, v68, v85
	v_max3_f32 v59, v92, v76, v93
	v_add_f32_e32 v132, v132, v2
	v_max3_f32 v41, v41, v69, v86
	v_max3_f32 v59, v59, v77, v94
	v_mfma_f32_32x32x16_bf16 v[20:35], v[46:49], v[164:167], v[20:35]
	s_nop 0
	v_max3_f32 v41, v41, v70, v87
	v_max3_f32 v41, v41, v71, v88
	v_max3_f32 v59, v59, v78, v95
	v_max3_f32 v41, v41, v72, v89
	v_max3_f32 v59, v59, v79, v96
	s_nop 0
	v_max3_f32 v41, v41, v73, v90
	v_max3_f32 v183, v41, v74, v91
	v_mfma_f32_32x32x16_bf16 v[4:19], v[50:53], v[242:245], v[4:19]
	v_add_f32_e32 v41, v132, v133
	v_max3_f32 v59, v59, v80, v97
	v_add_f32_e64 v36, v36, v40
	v_add_f32_e64 v37, v37, v41
	v_max3_f32 v59, v59, v81, v98
	v_max3_f32 v186, v59, v82, v99
	v_add_f32_e32 v59, v36, v37
	v_add_f32_e32 v36, v38, v58
	v_add_f32_e32 v37, v39, v59
	v_mfma_f32_32x32x16_bf16 v[20:35], v[50:53], v[160:163], v[20:35]
	v_add_f32_e32 v61, v36, v37
	v_add_f32_e32 v36, v124, v60
	v_add_f32_e32 v37, v125, v61
	v_add_f32_e32 v63, v36, v37
	v_add_f32_e32 v36, v126, v62
	v_add_f32_e32 v37, v127, v63
	v_add_f32_e32 v65, v36, v37
	v_add_f32_e32 v36, v128, v64
	v_add_f32_e32 v37, v129, v65
	v_mfma_f32_32x32x16_bf16 v[20:35], v[54:57], v[156:159], v[20:35]
	v_add_f32_e32 v67, v36, v37
	v_add_f32_e32 v36, v130, v66
	v_add_f32_e32 v37, v131, v67
	v_add_f32_e32 v185, v36, v37
	v_add_f32_e32 v36, v134, v184
	v_add_f32_e32 v37, v135, v185
	v_add_f32_e32 v2, v36, v37
	v_max3_f32 v36, v183, v75, v186
	v_add_f32_e32 v2, v209, v2
	v_mfma_f32_32x32x16_bf16 v[4:19], v[54:57], v[152:155], v[4:19]
	v_max3_f32 v36, v36, v83, v36
	s_nop 0
	v_mov_b32_e32 v38, v36
	s_nop 0
	s_nop 0
	v_permlane32_swap_b32_e32 v36, v38
	v_max3_f32 v36, v36, v38, v36
	s_nop 0
	v_cmp_lt_f32_e32 vcc, s56, v36
	s_cbranch_vccz .LBB0_1008
	s_nop 0
	v_add_f32_e32 v210, v180, v36
	v_cvt_pk_bf16_f32 v210, v210, v210
	v_lshlrev_b32_e32 v210, 16, v210
	v_cndmask_b32_e32 v210, v180, v210, vcc
	v_sub_f32_e32 v36, v180, v210
	v_sub_f32_e32 v186, v210, v180
	v_xor_b32_e32 v250, 0x80000000, v210
	v_min_f32_e32 v36, 0, v36
	v_lshrrev_b32_e32 v250, 16, v250
	v_exp_f32_e32 v36, v36
	v_cndmask_b32_e64 v250, 0, v250, s[2:3]
	s_and_saveexec_b64 s[14:15], s[2:3]
	ds_write_b32 v202, v36
	s_or_b64 exec, exec, s[14:15]
	v_mul_f32_e32 v2, v2, v36
	ds_read_b32 v36, v1
	ds_read_b32 v37, v1 offset:4
	ds_read_b32 v38, v1 offset:8
	ds_read_b32 v39, v1 offset:12
	ds_read_b32 v40, v1 offset:32
	ds_read_b32 v41, v1 offset:36
	ds_read_b32 v42, v1 offset:40
	ds_read_b32 v43, v1 offset:44
	ds_read_b32 v44, v1 offset:64
	ds_read_b32 v45, v1 offset:68
	ds_read_b32 v46, v1 offset:72
	ds_read_b32 v47, v1 offset:76
	ds_read_b32 v48, v1 offset:96
	ds_read_b32 v49, v1 offset:100
	ds_read_b32 v50, v1 offset:104
	ds_read_b32 v51, v1 offset:108
	s_waitcnt lgkmcnt(0)
	v_pk_mul_f32 v[20:21], v[20:21], v[36:37]
	v_pk_mul_f32 v[22:23], v[22:23], v[38:39]
	v_pk_mul_f32 v[24:25], v[24:25], v[40:41]
	v_pk_mul_f32 v[26:27], v[26:27], v[42:43]
	v_pk_mul_f32 v[28:29], v[28:29], v[44:45]
	v_pk_mul_f32 v[30:31], v[30:31], v[46:47]
	v_pk_mul_f32 v[32:33], v[32:33], v[48:49]
	v_pk_mul_f32 v[34:35], v[34:35], v[50:51]
	v_pk_mul_f32 v[4:5], v[4:5], v[36:37]
	v_pk_mul_f32 v[6:7], v[6:7], v[38:39]
	v_pk_mul_f32 v[8:9], v[8:9], v[40:41]
	v_pk_mul_f32 v[10:11], v[10:11], v[42:43]
	v_pk_mul_f32 v[12:13], v[12:13], v[44:45]
	v_pk_mul_f32 v[14:15], v[14:15], v[46:47]
	v_pk_mul_f32 v[16:17], v[16:17], v[48:49]
	v_pk_mul_f32 v[18:19], v[18:19], v[50:51]
	v_sub_f32_e32 v68, v68, v186
	v_sub_f32_e32 v69, v69, v186
	v_sub_f32_e32 v70, v70, v186
	v_sub_f32_e32 v71, v71, v186
	v_sub_f32_e32 v72, v72, v186
	v_sub_f32_e32 v73, v73, v186
	v_sub_f32_e32 v74, v74, v186
	v_sub_f32_e32 v75, v75, v186
	v_sub_f32_e32 v76, v76, v186
	v_sub_f32_e32 v77, v77, v186
	v_sub_f32_e32 v78, v78, v186
	v_sub_f32_e32 v79, v79, v186
	v_sub_f32_e32 v80, v80, v186
	v_sub_f32_e32 v81, v81, v186
	v_sub_f32_e32 v82, v82, v186
	v_sub_f32_e32 v83, v83, v186
	v_sub_f32_e32 v84, v84, v186
	v_sub_f32_e32 v85, v85, v186
	v_sub_f32_e32 v86, v86, v186
	v_sub_f32_e32 v87, v87, v186
	v_sub_f32_e32 v88, v88, v186
	v_sub_f32_e32 v89, v89, v186
	v_sub_f32_e32 v90, v90, v186
	v_sub_f32_e32 v91, v91, v186
	v_sub_f32_e32 v92, v92, v186
	v_sub_f32_e32 v93, v93, v186
	v_sub_f32_e32 v94, v94, v186
	v_sub_f32_e32 v95, v95, v186
	v_sub_f32_e32 v96, v96, v186
	v_sub_f32_e32 v97, v97, v186
	v_sub_f32_e32 v98, v98, v186
	v_sub_f32_e32 v99, v99, v186
	s_mov_b32 s56, 0x41000000
	s_branch .LBB0_1009
